# chunk-prep units remapped to the workgroup that produced their q/k/v chunks; device-wide barrier between conv and prep replaced by a workgroup barrier
# speedup vs baseline: 1.0408x; 1.0082x over previous
; __device__ __forceinline__ unsigned xb_ld(unsigned* p)              { return __hip_atomic_load(p, __ATOMIC_RELAXED, __HIP_MEMORY_SCOPE_AGENT); }
; __device__ __forceinline__ unsigned xb_add(unsigned* p, unsigned v) { return __hip_atomic_fetch_add(p, v, __ATOMIC_RELAXED, __HIP_MEMORY_SCOPE_AGENT); }
; #define XB_SPIN(cond, bar) do { unsigned _sp = 0; while (cond) { __builtin_amdgcn_s_sleep(1); \
;     if ((++_sp & 255u) == 0u) { if (xb_ld(&(bar)[XB_TMO])) break; if (_sp > XB_SPIN_CAP) { atomicAdd(&(bar)[XB_TMO], 1u); break; } } } } while (0)
; __device__ __forceinline__ void xcd_barrier(const XcdBarrier& b) {
;     asm volatile("s_waitcnt vmcnt(0)" ::: "memory");
;     __syncthreads();
;     if (threadIdx.x == 0) {
;         unsigned* bar = b.bar;
;         __builtin_amdgcn_s_waitcnt(0);
;         unsigned nloc = b.st[0], nx = b.st[1];
;         if (nloc == 0u) { xcd_barrier_complete(bar, b.x, nloc, nx); b.st[0] = nloc; b.st[1] = nx; }
;         const unsigned old = xb_add(&bar[XB_XSUB(b.x)], 1u);
;         const unsigned gen = old / nloc;
;         if (old + 1u == (gen + 1u) * nloc) {
;             __builtin_amdgcn_fence(__ATOMIC_RELEASE, "agent");
;             asm volatile("s_waitcnt vmcnt(0)" ::: "memory");
;             const unsigned og = xb_add(&bar[XB_TOP], 1u);
;             const unsigned tg = og / nx;
;             if (og + 1u == (tg + 1u) * nx) xb_add(&bar[XB_TOPGEN], 1u);
;             else XB_SPIN(xb_ld(&bar[XB_TOPGEN]) == tg, bar);
;             __builtin_amdgcn_fence(__ATOMIC_ACQUIRE, "agent");
;             xb_add(&bar[XB_XGEN(b.x)], 1u);
;             asm volatile("s_waitcnt vmcnt(0)" ::: "memory");
;         } else {
;             XB_SPIN(xb_ld(&bar[XB_XGEN(b.x)]) == gen, bar);
;             __builtin_amdgcn_fence(__ATOMIC_ACQUIRE, "agent");
;             asm volatile("s_waitcnt vmcnt(0)" ::: "memory");
;         }
;     }
;     __syncthreads();
; }
.LBB0_197:
	s_waitcnt vmcnt(0)
	s_barrier
	s_mov_b64 s[0:1], exec
	v_readlane_b32 s4, v253, 37
	v_readlane_b32 s5, v253, 38
	s_and_b64 s[4:5], s[0:1], s[4:5]
	s_mov_b64 exec, s[4:5]
	s_branch .LBB0_249
	s_add_i32 s4, 0, 0x20000
	v_mov_b32_e32 v0, s4
	s_waitcnt vmcnt(0) expcnt(0) lgkmcnt(0)
	ds_read_b32 v2, v0
	s_add_i32 s4, 0, 0x20004
	v_mov_b32_e32 v0, s4
	ds_read_b32 v0, v0
	s_waitcnt lgkmcnt(1)
	v_cmp_ne_u32_e32 vcc, 0, v2
	s_cbranch_vccnz .LBB0_213
	v_readlane_b32 s4, v253, 0
	s_mul_i32 s33, s81, s4
	s_add_u32 s4, s16, 0x1e00200
	s_addc_u32 s5, s17, 0
	s_add_u32 s6, s16, 0x1e00400
	s_addc_u32 s7, s17, 0
	s_add_u32 s8, s16, 0x1e00500
	s_addc_u32 s9, s17, 0
	s_add_u32 s10, s16, 0x1e00600
	s_addc_u32 s11, s17, 0
	s_add_u32 s12, s16, 0x1e00700
	s_addc_u32 s13, s17, 0
	s_add_u32 s14, s16, 0x1e00800
	s_addc_u32 s15, s17, 0
	s_add_u32 s18, s16, 0x1e00900
	s_addc_u32 s19, s17, 0
	s_add_u32 s20, s16, 0x1e00a00
	s_addc_u32 s21, s17, 0
	s_add_u32 s22, s16, 0x1e00b00
	s_addc_u32 s23, s17, 0
	s_add_u32 s24, s16, 0x1e00c00
	s_addc_u32 s25, s17, 0
	s_add_u32 s26, s16, 0x1e00d00
	s_addc_u32 s27, s17, 0
	s_add_u32 s28, s16, 0x1e00e00
	s_addc_u32 s29, s17, 0
	s_add_u32 s30, s16, 0x1e00f00
	s_addc_u32 s31, s17, 0
	s_add_u32 s34, s16, 0x1e01000
	s_addc_u32 s35, s17, 0
	s_add_u32 s36, s16, 0x1e01100
	s_addc_u32 s37, s17, 0
	s_add_u32 s38, s16, 0x1e01200
	s_addc_u32 s39, s17, 0
	s_add_u32 s40, s16, 0x1e01300
	s_mul_i32 s33, s33, s80
	s_addc_u32 s41, s17, 0
	s_mov_b32 s48, 1
	v_mov_b32_e32 v16, 0
	s_branch .LBB0_201

; #define PG8_LAS __attribute__((address_space(3)))
; __device__ __forceinline__ void phase_prep(const Args& a, PG8_LAS unsigned char* lds) {
;     const int tid = threadIdx.x, lane = tid & 63, wave = __builtin_amdgcn_readfirstlane(tid >> 6), half = wave >> 2, lw = wave & 3, q = lane >> 4, r = lane & 15;
;     const int role = (lw - half) & 3;
;     PG8_LAS unsigned char* hb = lds + half * 36864;
;     PG8_LAS float* sG = (PG8_LAS float*)hb; PG8_LAS float* sB = sG + 64; PG8_LAS float* sE = sG + 128; PG8_LAS float* sK = sG + 192; PG8_LAS float* sL = sG + 256;
;     PG8_LAS unsigned char* Tu = hb + 17408; PG8_LAS unsigned char* Tw = Tu + 9216;
;     const bf16_t* qb = (const bf16_t*)(a.ws + WS_QB); const bf16_t* kb = (const bf16_t*)(a.ws + WS_KB);
;     const bf16_t* kT = (const bf16_t*)(a.ws + WS_KT); const bf16_t* vT = (const bf16_t*)(a.ws + WS_VT);
;     const float* betaB = (const float*)(a.ws + WS_BETA); const float* gB = (const float*)(a.ws + WS_G); float* glast = (float*)(a.ws + WS_GL);
;     for (int unit = blockIdx.x; unit < 1024; unit += gridDim.x) {
;         const int hp = unit & 1, bn = unit >> 1, h = 2 * hp + half, item = bn * 4 + h; const size_t r0 = (size_t)bn * 64;
;         unsigned char* pi = a.ws + WS_PREP + (size_t)item * PREP_ITEM;
;         bf16_t* wp = (bf16_t*)(pi + PI_W); bf16_t* qgp = (bf16_t*)(pi + PI_QG); bf16_t* kdTp = (bf16_t*)(pi + PI_KD); bf16_t* uT = (bf16_t*)(pi + PI_UT); bf16_t* aqkp = (bf16_t*)(pi + PI_AQ);
;         const bf16_t* qbase = qb + r0 * 512 + h * 128; const bf16_t* kbase = kb + r0 * 512 + h * 128;
;         const bf16_t* kTb = kT + ((size_t)bn * 512 + h * 128) * 64; const bf16_t* vTb = vT + ((size_t)bn * 512 + h * 128) * 64;
;         bf16x8 ak[4], aq[4], bkf[2][4];
; #pragma unroll
;         for (int s = 0; s < 4; ++s) { ak[s] = *(const bf16x8*)(kbase + (size_t)(16 * lw + r) * 512 + 32 * s + 8 * q); aq[s] = *(const bf16x8*)(qbase + (size_t)(16 * lw + r) * 512 + 32 * s + 8 * q); }
; #pragma unroll
;         for (int tj = 0; tj < 2; ++tj)
; #pragma unroll
;             for (int s = 0; s < 4; ++s) bkf[tj][s] = *(const bf16x8*)(kbase + (size_t)(16 * tj + r) * 512 + 32 * s + 8 * q);
;         bf16x8 pv[2][2], pk[2][2];
;         if (role != 0) {
; #pragma unroll
;         for (int cc = 0; cc < 2; ++cc) { const int ct = 2 * lw + cc;
.LBB0_249:
	s_or_b64 exec, exec, s[0:1]
	s_add_u32 s10, s16, 0x2000000
	s_addc_u32 s11, s17, 0
	v_readlane_b32 s0, v253, 17
	s_bitcmp0_b32 s0, 3
	s_waitcnt lgkmcnt(0)
	s_barrier
	s_cbranch_scc1 .LBB0_301
	s_cmpk_gt_i32 s82, 0x3ff
	v_readfirstlane_b32 s0, v152
	s_cbranch_scc1 .LBB0_301
	v_mbcnt_lo_u32_b32 v0, -1, 0
	s_waitcnt vmcnt(14)
	v_mbcnt_hi_u32_b32 v7, -1, v0
	s_waitcnt vmcnt(12)
	v_and_b32_e32 v9, 64, v7
	s_waitcnt vmcnt(7)
	v_add_u32_e32 v16, -1, v7
	v_cmp_lt_i32_e32 vcc, v16, v9
	v_and_b32_e32 v1, 63, v152
	v_bfrev_b32_e32 v0, 0.5
	v_cndmask_b32_e32 v16, v16, v7, vcc
	v_lshlrev_b32_e32 v131, 2, v16
	v_add_u32_e32 v16, -2, v7
	v_cmp_lt_i32_e32 vcc, v16, v9
	v_lshl_or_b32 v99, v7, 2, v0
	s_lshr_b32 s1, s0, 6
	v_cndmask_b32_e32 v16, v16, v7, vcc
	v_lshlrev_b32_e32 v132, 2, v16
	v_add_u32_e32 v16, -4, v7
	v_cmp_lt_i32_e32 vcc, v16, v9
	s_lshr_b32 s33, s0, 8
	v_writelane_b32 v253, s76, 39
	v_cndmask_b32_e32 v16, v16, v7, vcc
	v_lshlrev_b32_e32 v133, 2, v16
	v_add_u32_e32 v16, -8, v7
	v_cmp_lt_i32_e32 vcc, v16, v9
	s_sub_i32 s1, s1, s33
	v_writelane_b32 v253, s77, 40
	v_cndmask_b32_e32 v16, v16, v7, vcc
	v_lshlrev_b32_e32 v134, 2, v16
	v_add_u32_e32 v16, -16, v7
	v_cmp_lt_i32_e32 vcc, v16, v9
	s_and_b32 s28, s1, 3
	s_mul_i32 s1, s33, 0x9000
	v_cndmask_b32_e32 v16, v16, v7, vcc
	v_lshlrev_b32_e32 v135, 2, v16
	v_subrev_u32_e32 v16, 32, v7
	v_cmp_lt_i32_e32 vcc, v16, v9
	v_writelane_b32 v253, s78, 41
	s_add_i32 s4, s1, 0
	v_cndmask_b32_e32 v7, v16, v7, vcc
	v_cmp_eq_u32_e32 vcc, 1, v1
	v_writelane_b32 v253, s79, 42
	s_add_u32 s1, s16, 0x10000000
	v_cndmask_b32_e64 v140, 0, 1.0, vcc
	v_cmp_eq_u32_e32 vcc, 2, v1
	v_writelane_b32 v253, s1, 43
	s_addc_u32 s1, s17, 0
	v_cndmask_b32_e64 v141, 0, 1.0, vcc
	v_cmp_eq_u32_e32 vcc, 3, v1
	v_writelane_b32 v253, s1, 44
	s_add_u32 s1, s16, 0x12000000
	v_cndmask_b32_e64 v142, 0, 1.0, vcc
	v_cmp_eq_u32_e32 vcc, 4, v1
	v_writelane_b32 v253, s1, 45
	s_addc_u32 s1, s17, 0
	v_cndmask_b32_e64 v143, 0, 1.0, vcc
	v_cmp_eq_u32_e32 vcc, 5, v1
	v_writelane_b32 v253, s1, 46
	s_add_u32 s1, s16, 0x4000000
	v_cndmask_b32_e64 v144, 0, 1.0, vcc
	v_cmp_eq_u32_e32 vcc, 6, v1
	v_writelane_b32 v253, s1, 47
	s_addc_u32 s1, s17, 0
	v_cndmask_b32_e64 v145, 0, 1.0, vcc
	v_cmp_eq_u32_e32 vcc, 7, v1
	s_add_u32 s6, s16, 0x1800000
	s_addc_u32 s7, s17, 0
	v_cndmask_b32_e64 v146, 0, 1.0, vcc
	v_cmp_eq_u32_e32 vcc, 8, v1
	v_writelane_b32 v253, s1, 48
	s_add_u32 s8, s16, 0x1880000
	v_cndmask_b32_e64 v147, 0, 1.0, vcc
	v_cmp_eq_u32_e32 vcc, 9, v1
	v_writelane_b32 v253, s6, 49
	s_addc_u32 s9, s17, 0
	v_cndmask_b32_e64 v148, 0, 1.0, vcc
	v_cmp_eq_u32_e32 vcc, 10, v1
	v_writelane_b32 v253, s7, 50
	s_add_u32 s1, s16, 0x1b00000
	v_cndmask_b32_e64 v149, 0, 1.0, vcc
	v_cmp_eq_u32_e32 vcc, 11, v1
	v_writelane_b32 v253, s1, 51
	s_addc_u32 s1, s17, 0
	v_cndmask_b32_e64 v150, 0, 1.0, vcc
	v_cmp_eq_u32_e32 vcc, 12, v1
	s_bfe_u32 s0, s0, 0x20006
	s_cmp_lg_u32 s28, 0
	v_cndmask_b32_e64 v151, 0, 1.0, vcc
	v_cmp_eq_u32_e32 vcc, 13, v1
	v_writelane_b32 v253, s1, 52
	s_cselect_b64 s[6:7], -1, 0
	v_cndmask_b32_e64 v154, 0, 1.0, vcc
	v_cmp_eq_u32_e32 vcc, 14, v1
	v_writelane_b32 v253, s6, 53
	s_cmp_eq_u32 s0, 0
	v_cndmask_b32_e64 v155, 0, 1.0, vcc
	v_cmp_eq_u32_e32 vcc, 15, v1
	v_writelane_b32 v253, s7, 54
	s_cselect_b64 s[6:7], -1, 0
	v_cndmask_b32_e64 v156, 0, 1.0, vcc
	v_cmp_eq_u32_e32 vcc, 16, v1
	v_mov_b32_e32 v97, 0
	v_writelane_b32 v253, s6, 55
	v_cndmask_b32_e64 v157, 0, 1.0, vcc
	v_cmp_eq_u32_e32 vcc, 17, v1
	v_and_b32_e32 v3, 15, v152
	v_bfe_u32 v5, v152, 4, 2
	v_cndmask_b32_e64 v158, 0, 1.0, vcc
	v_cmp_eq_u32_e32 vcc, 18, v1
	v_writelane_b32 v253, s7, 56
	v_cmp_eq_u32_sdwa s[6:7], v152, v97 src0_sel:BYTE_0 src1_sel:DWORD
	v_cndmask_b32_e64 v159, 0, 1.0, vcc
	v_cmp_eq_u32_e32 vcc, 19, v1
	v_lshlrev_b32_e32 v11, 1, v152
	v_and_b32_e32 v0, 3, v152
	v_cndmask_b32_e64 v160, 0, 1.0, vcc
	v_cmp_eq_u32_e32 vcc, 20, v1
	s_lshl_b32 s1, s0, 6
	v_lshlrev_b32_e32 v6, 9, v3
	v_cndmask_b32_e64 v161, 0, 1.0, vcc
	v_cmp_eq_u32_e32 vcc, 21, v1
	v_lshlrev_b32_e32 v12, 3, v5
	v_writelane_b32 v253, s6, 57
	v_cndmask_b32_e64 v162, 0, 1.0, vcc
	v_cmp_eq_u32_e32 vcc, 22, v1
	v_and_or_b32 v13, v11, 24, v0
	v_lshlrev_b32_e32 v0, 2, v5
	v_cndmask_b32_e64 v163, 0, 1.0, vcc
	v_cmp_eq_u32_e32 vcc, 23, v1
	s_add_i32 s1, s4, s1
	v_and_b32_e32 v2, 48, v152
	v_cndmask_b32_e64 v164, 0, 1.0, vcc
	v_cmp_eq_u32_e32 vcc, 24, v1
	v_lshl_or_b32 v4, s28, 6, v1
	v_lshlrev_b32_e32 v10, 6, v3
	v_cndmask_b32_e64 v165, 0, 1.0, vcc
	v_cmp_eq_u32_e32 vcc, 25, v1
	v_lshl_or_b32 v8, s0, 13, v6
	v_writelane_b32 v253, s7, 58
	v_cndmask_b32_e64 v166, 0, 1.0, vcc
	v_cmp_eq_u32_e32 vcc, 26, v1
	v_lshl_or_b32 v33, s0, 4, v0
	v_add_u32_e32 v15, s1, v2
	v_add_u32_e32 v96, 0xffffff80, v4
	v_lshl_or_b32 v4, s0, 5, v12
	v_lshl_or_b32 v10, s0, 11, v10
	v_cmp_gt_u32_e64 s[0:1], 2, v1
	v_cndmask_b32_e64 v167, 0, 1.0, vcc
	v_cmp_eq_u32_e32 vcc, 27, v1
	v_writelane_b32 v253, s0, 59
	v_or_b32_e32 v35, 1, v33
	v_cndmask_b32_e64 v168, 0, 1.0, vcc
	v_cmp_eq_u32_e32 vcc, 28, v1
	v_writelane_b32 v253, s1, 60
	v_cmp_gt_u32_e64 s[0:1], 4, v1
	v_cndmask_b32_e64 v169, 0, 1.0, vcc
	v_cmp_eq_u32_e32 vcc, 29, v1
	v_writelane_b32 v253, s0, 61
	v_or_b32_e32 v37, 2, v33
	v_cndmask_b32_e64 v170, 0, 1.0, vcc
	v_cmp_eq_u32_e32 vcc, 30, v1
	v_writelane_b32 v253, s1, 62
	v_cmp_gt_u32_e64 s[0:1], 8, v1
	v_cndmask_b32_e64 v171, 0, 1.0, vcc
	v_cmp_eq_u32_e32 vcc, 31, v1
	v_writelane_b32 v253, s0, 63
	v_or_b32_e32 v39, 3, v33
	v_cndmask_b32_e64 v172, 0, 1.0, vcc
	v_cmp_eq_u32_e32 vcc, 32, v1
	v_writelane_b32 v252, s1, 0
	v_cmp_gt_u32_e64 s[0:1], 16, v1
	v_cndmask_b32_e64 v173, 0, 1.0, vcc
	v_cmp_eq_u32_e32 vcc, 33, v1
	v_writelane_b32 v252, s0, 1
	v_or_b32_e32 v25, 16, v3
	v_cndmask_b32_e64 v174, 0, 1.0, vcc
	v_cmp_eq_u32_e32 vcc, 34, v1
	v_writelane_b32 v252, s1, 2
	v_cmp_gt_u32_e64 s[0:1], 32, v1
	v_cndmask_b32_e64 v175, 0, 1.0, vcc
	v_cmp_eq_u32_e32 vcc, 35, v1
	v_writelane_b32 v252, s0, 3
	v_lshlrev_b32_e32 v136, 2, v7
	v_cndmask_b32_e64 v176, 0, 1.0, vcc
	v_cmp_eq_u32_e32 vcc, 36, v1
	v_writelane_b32 v252, s1, 4
	v_cmp_ge_u32_e64 s[0:1], v33, v3
	v_cndmask_b32_e64 v177, 0, 1.0, vcc
	v_cmp_eq_u32_e32 vcc, 37, v1
	v_writelane_b32 v252, s0, 5
	v_lshlrev_b32_e32 v7, 6, v33
	v_cndmask_b32_e64 v178, 0, 1.0, vcc
	v_cmp_eq_u32_e32 vcc, 38, v1
	v_writelane_b32 v252, s1, 6
	v_cmp_gt_u32_e64 s[0:1], v33, v3
	v_cndmask_b32_e64 v179, 0, 1.0, vcc
	v_cmp_eq_u32_e32 vcc, 39, v1
	v_writelane_b32 v252, s0, 7
	v_lshlrev_b32_e32 v9, 6, v35
	v_cndmask_b32_e64 v180, 0, 1.0, vcc
	v_cmp_eq_u32_e32 vcc, 40, v1
	v_writelane_b32 v252, s1, 8
	v_cmp_lt_u32_e64 s[0:1], v35, v3
	v_cndmask_b32_e64 v181, 0, 1.0, vcc
	v_cmp_eq_u32_e32 vcc, 41, v1
	v_writelane_b32 v252, s0, 9
	s_waitcnt vmcnt(4)
; #define PG8_LAS __attribute__((address_space(3)))
; __device__ __forceinline__ void phase_prep(const Args& a, PG8_LAS unsigned char* lds) {
;     const int tid = threadIdx.x, lane = tid & 63, wave = __builtin_amdgcn_readfirstlane(tid >> 6), half = wave >> 2, lw = wave & 3, q = lane >> 4, r = lane & 15;
;     const int role = (lw - half) & 3;
;     PG8_LAS unsigned char* hb = lds + half * 36864;
;     PG8_LAS float* sG = (PG8_LAS float*)hb; PG8_LAS float* sB = sG + 64; PG8_LAS float* sE = sG + 128; PG8_LAS float* sK = sG + 192; PG8_LAS float* sL = sG + 256;
;     PG8_LAS unsigned char* Tu = hb + 17408; PG8_LAS unsigned char* Tw = Tu + 9216;
;     const bf16_t* qb = (const bf16_t*)(a.ws + WS_QB); const bf16_t* kb = (const bf16_t*)(a.ws + WS_KB);
;     const bf16_t* kT = (const bf16_t*)(a.ws + WS_KT); const bf16_t* vT = (const bf16_t*)(a.ws + WS_VT);
;     const float* betaB = (const float*)(a.ws + WS_BETA); const float* gB = (const float*)(a.ws + WS_G); float* glast = (float*)(a.ws + WS_GL);
;     for (int unit = blockIdx.x; unit < 1024; unit += gridDim.x) {
;         const int hp = unit & 1, bn = unit >> 1, h = 2 * hp + half, item = bn * 4 + h; const size_t r0 = (size_t)bn * 64;
;         unsigned char* pi = a.ws + WS_PREP + (size_t)item * PREP_ITEM;
;         bf16_t* wp = (bf16_t*)(pi + PI_W); bf16_t* qgp = (bf16_t*)(pi + PI_QG); bf16_t* kdTp = (bf16_t*)(pi + PI_KD); bf16_t* uT = (bf16_t*)(pi + PI_UT); bf16_t* aqkp = (bf16_t*)(pi + PI_AQ);
;         const bf16_t* qbase = qb + r0 * 512 + h * 128; const bf16_t* kbase = kb + r0 * 512 + h * 128;
;         const bf16_t* kTb = kT + ((size_t)bn * 512 + h * 128) * 64; const bf16_t* vTb = vT + ((size_t)bn * 512 + h * 128) * 64;
;         bf16x8 ak[4], aq[4], bkf[2][4];
; #pragma unroll
;         for (int s = 0; s < 4; ++s) { ak[s] = *(const bf16x8*)(kbase + (size_t)(16 * lw + r) * 512 + 32 * s + 8 * q); aq[s] = *(const bf16x8*)(qbase + (size_t)(16 * lw + r) * 512 + 32 * s + 8 * q); }
	v_lshlrev_b32_e32 v19, 6, v37
	v_cndmask_b32_e64 v182, 0, 1.0, vcc
	v_cmp_eq_u32_e32 vcc, 42, v1
	v_writelane_b32 v252, s1, 10
	v_cmp_ge_u32_e64 s[0:1], v35, v3
	v_cndmask_b32_e64 v183, 0, 1.0, vcc
	v_cmp_eq_u32_e32 vcc, 43, v1
	v_writelane_b32 v252, s0, 11
	s_waitcnt vmcnt(2)
	v_lshlrev_b32_e32 v21, 6, v39
	v_cndmask_b32_e64 v184, 0, 1.0, vcc
	v_cmp_eq_u32_e32 vcc, 44, v1
	v_writelane_b32 v252, s1, 12
	v_cmp_lt_u32_e64 s[0:1], v37, v3
	v_cndmask_b32_e64 v185, 0, 1.0, vcc
	v_cmp_eq_u32_e32 vcc, 45, v1
	v_writelane_b32 v252, s0, 13
	v_or_b32_e32 v27, 4, v13
	v_cndmask_b32_e64 v186, 0, 1.0, vcc
	v_cmp_eq_u32_e32 vcc, 46, v1
	v_writelane_b32 v252, s1, 14
	v_cmp_ge_u32_e64 s[0:1], v37, v3
	v_cndmask_b32_e64 v187, 0, 1.0, vcc
	v_cmp_eq_u32_e32 vcc, 47, v1
	v_writelane_b32 v252, s0, 15
	v_or_b32_e32 v16, v7, v13
	v_cndmask_b32_e64 v188, 0, 1.0, vcc
	v_cmp_eq_u32_e32 vcc, 48, v1
	v_writelane_b32 v252, s1, 16
	v_cmp_gt_u32_e64 s[0:1], v37, v3
	v_cndmask_b32_e64 v189, 0, 1.0, vcc
	v_cmp_eq_u32_e32 vcc, 49, v1
	v_writelane_b32 v252, s0, 17
	v_or_b32_e32 v18, v9, v13
	v_cndmask_b32_e64 v190, 0, 1.0, vcc
	v_cmp_eq_u32_e32 vcc, 50, v1
	v_writelane_b32 v252, s1, 18
	v_cmp_lt_u32_e64 s[0:1], v39, v3
	v_cndmask_b32_e64 v191, 0, 1.0, vcc
	v_cmp_eq_u32_e32 vcc, 51, v1
	v_writelane_b32 v252, s0, 19
	v_or_b32_e32 v20, v19, v13
	v_cndmask_b32_e64 v192, 0, 1.0, vcc
	v_cmp_eq_u32_e32 vcc, 52, v1
	v_writelane_b32 v252, s1, 20
	v_cmp_ge_u32_e64 s[0:1], v39, v3
	v_cndmask_b32_e64 v193, 0, 1.0, vcc
	v_cmp_eq_u32_e32 vcc, 53, v1
	v_writelane_b32 v252, s0, 21
	v_or_b32_e32 v22, v21, v13
	v_cndmask_b32_e64 v194, 0, 1.0, vcc
	v_cmp_eq_u32_e32 vcc, 54, v1
	v_writelane_b32 v252, s1, 22
	v_cmp_gt_u32_e64 s[0:1], v39, v3
	v_cndmask_b32_e64 v195, 0, 1.0, vcc
	v_cmp_eq_u32_e32 vcc, 55, v1
	v_writelane_b32 v252, s0, 23
	v_or_b32_e32 v24, v7, v27
	v_cndmask_b32_e64 v196, 0, 1.0, vcc
	v_cmp_eq_u32_e32 vcc, 56, v1
	v_writelane_b32 v252, s1, 24
	v_cmp_ge_u32_e64 s[0:1], v33, v25
	v_cndmask_b32_e64 v197, 0, 1.0, vcc
	v_cmp_eq_u32_e32 vcc, 57, v1
	v_writelane_b32 v252, s0, 25
	v_or_b32_e32 v26, v9, v27
	v_or_b32_e32 v28, v19, v27
	v_or_b32_e32 v30, v21, v27
	v_or_b32_e32 v27, 32, v13
	v_or_b32_e32 v13, 36, v13
	v_cndmask_b32_e64 v198, 0, 1.0, vcc
	v_cmp_eq_u32_e32 vcc, 58, v1
	v_add_u32_e32 v17, s4, v2
	v_lshlrev_b32_e32 v2, 7, v3
	v_lshl_add_u32 v137, v3, 2, s4
	v_cmp_lt_u32_e64 s[12:13], v33, v3
	v_lshlrev_b32_e32 v23, 8, v3
	v_writelane_b32 v252, s1, 26
	v_cmp_gt_u32_e64 s[0:1], v33, v25
	v_or_b32_e32 v41, 32, v3
	v_or_b32_e32 v34, v9, v27
	v_or_b32_e32 v43, 48, v3
	v_or_b32_e32 v42, v9, v13
	v_cndmask_b32_e64 v199, 0, 1.0, vcc
	v_cmp_eq_u32_e32 vcc, 59, v1
	v_mul_u32_u24_e32 v9, 0x90, v3
	v_lshlrev_b32_e32 v3, 4, v3
	v_writelane_b32 v252, s0, 27
	v_cndmask_b32_e64 v200, 0, 1.0, vcc
	v_cmp_eq_u32_e32 vcc, 60, v1
	v_lshl_or_b32 v102, v5, 10, v3
	v_add_u32_e32 v3, s4, v0
	v_writelane_b32 v252, s1, 28
	v_cmp_lt_u32_e64 s[0:1], v35, v25
	v_cndmask_b32_e64 v201, 0, 1.0, vcc
	v_cmp_eq_u32_e32 vcc, 61, v1
	v_add_u32_e32 v206, 0x200, v3
	v_lshlrev_b32_e32 v3, 4, v152
	v_writelane_b32 v252, s0, 29
	v_cndmask_b32_e64 v202, 0, 1.0, vcc
	v_cmp_eq_u32_e32 vcc, 62, v1
	s_add_u32 s29, s16, 0x16000000
	v_and_b32_e32 v3, 0xc0, v3
	v_lshlrev_b32_e32 v98, 2, v1
	v_writelane_b32 v252, s1, 30
	v_cmp_eq_u32_e64 s[62:63], 0, v1
	v_cndmask_b32_e64 v203, 0, 1.0, vcc
	v_cmp_eq_u32_e32 vcc, 63, v1
	v_lshl_add_u32 v205, v1, 1, s4
	v_or_b32_e32 v1, 0x1f80, v11
	s_addc_u32 s30, s17, 0
	s_lshl_b32 s0, s33, 7
	v_lshl_or_b32 v3, v5, 8, v3
	v_and_b32_e32 v5, 1, v152
	v_lshlrev_b32_e32 v11, 2, v152
	v_writelane_b32 v252, s0, 31
	v_lshlrev_b32_e32 v5, 5, v5
	v_and_b32_e32 v11, 8, v11
	v_lshlrev_b64 v[100:101], 7, v[96:97]
	v_lshlrev_b32_e32 v14, 6, v96
	v_cmp_lt_u32_e64 s[36:37], v33, v25
	v_cmp_ge_u32_e64 s[44:45], v35, v25
	v_cmp_lt_u32_e64 s[46:47], v37, v25
	v_cmp_ge_u32_e64 s[48:49], v37, v25
	v_cmp_gt_u32_e64 s[50:51], v37, v25
	v_cmp_lt_u32_e64 s[52:53], v39, v25
	v_cmp_ge_u32_e64 s[54:55], v39, v25
	v_cmp_gt_u32_e64 s[56:57], v39, v25
	v_lshlrev_b32_e32 v25, 8, v25
	v_or_b32_e32 v32, v7, v27
	v_or_b32_e32 v36, v19, v27
	v_or_b32_e32 v38, v21, v27
	v_lshlrev_b32_e32 v27, 8, v41
	v_or_b32_e32 v40, v7, v13
	v_or_b32_e32 v44, v19, v13
	v_or_b32_e32 v46, v21, v13
	v_lshlrev_b32_e32 v7, 8, v43
	v_or_b32_e32 v48, 0x800, v2
	v_or_b32_e32 v50, 0x1000, v2
	v_or_b32_e32 v52, 0x1800, v2
	v_or3_b32 v96, v3, v5, v11
	s_mov_b64 s[0:1], 0x16004800
	v_writelane_b32 v252, s4, 32
	s_mov_b32 s15, 0
	v_add_u32_e32 v130, s4, v98
	v_lshl_add_u32 v138, v33, 2, s4
	v_cmp_lt_u32_e64 s[58:59], v33, v41
	v_cmp_ge_u32_e64 s[60:61], v33, v41
	v_cndmask_b32_e64 v139, 0, 1.0, s[62:63]
	v_cndmask_b32_e64 v204, 0, 1.0, vcc
	v_mov_b32_e32 v103, v97
	s_lshl_b32 s31, s82, 3
	s_mov_b64 s[74:75], s[80:81]
	s_mov_b32 s34, 2
	v_lshl_add_u64 v[104:105], v[96:97], 0, s[0:1]
	v_lshlrev_b32_e32 v106, 1, v8
	v_lshlrev_b32_e32 v96, 1, v12
	v_lshlrev_b32_e32 v108, 1, v6
	v_lshlrev_b32_e32 v207, 1, v16
	v_lshlrev_b32_e32 v208, 1, v18
	v_lshlrev_b32_e32 v209, 1, v20
	v_lshlrev_b32_e32 v210, 1, v22
	v_add_u32_e32 v211, v15, v23
	v_lshlrev_b32_e32 v212, 1, v24
	v_lshlrev_b32_e32 v213, 1, v26
	v_lshlrev_b32_e32 v214, 1, v28
	v_lshlrev_b32_e32 v215, 1, v30
	v_add_u32_e32 v216, v15, v25
	v_lshlrev_b32_e32 v217, 1, v32
	v_lshlrev_b32_e32 v218, 1, v34
	v_lshlrev_b32_e32 v219, 1, v36
	v_lshlrev_b32_e32 v220, 1, v38
	v_add_u32_e32 v221, v15, v27
	s_mov_b32 s35, 0xc000
	v_lshlrev_b32_e32 v222, 1, v40
	v_lshlrev_b32_e32 v223, 1, v42
	v_lshlrev_b32_e32 v224, 1, v44
	v_lshlrev_b32_e32 v225, 1, v46
	v_add_u32_e32 v226, v15, v7
	v_lshlrev_b32_e32 v110, 1, v14
	v_add_u32_e32 v227, s4, v1
	v_add_u32_e32 v228, v17, v9
	v_lshlrev_b32_e32 v112, 1, v0
	v_lshlrev_b32_e32 v114, 1, v10
	v_lshlrev_b32_e32 v116, 1, v4
	v_lshlrev_b32_e32 v118, 1, v2
	v_lshlrev_b32_e32 v120, 1, v48
	v_lshlrev_b32_e32 v122, 1, v50
	v_lshlrev_b32_e32 v124, 1, v52
	v_mov_b32_e32 v229, 0x12000
	v_writelane_b32 v252, s82, 33
	s_lshl_b32 s38, s82, 2
	s_add_i32 s98, s38, 4
	v_cmp_gt_u32_e64 s[64:65], v33, v41
	v_cmp_lt_u32_e64 s[66:67], v35, v41
	v_cmp_ge_u32_e64 s[68:69], v35, v41
	v_cmp_lt_u32_e64 s[70:71], v37, v41
	v_cmp_ge_u32_e64 s[72:73], v37, v41
	v_cmp_gt_u32_e64 s[42:43], v37, v41
	v_cmp_lt_u32_e64 s[76:77], v39, v41
	v_cmp_ge_u32_e64 s[78:79], v39, v41
	v_cmp_gt_u32_e64 s[80:81], v39, v41
	v_cmp_lt_u32_e64 s[82:83], v33, v43
	v_cmp_ge_u32_e64 s[84:85], v33, v43
	v_cmp_gt_u32_e64 s[86:87], v33, v43
	v_cmp_lt_u32_e64 s[88:89], v35, v43
	v_cmp_ge_u32_e64 s[90:91], v35, v43
	v_cmp_lt_u32_e64 s[92:93], v37, v43
	v_cmp_ge_u32_e64 s[94:95], v37, v43
	v_cmp_gt_u32_e64 s[96:97], v37, v43
	v_cmp_lt_u32_e64 s[0:1], v39, v43
	v_cmp_ge_u32_e64 s[6:7], v39, v43
	v_cmp_gt_u32_e64 s[4:5], v39, v43
	s_branch .LBB0_253
; #define PG8_LAS __attribute__((address_space(3)))
; __device__ __forceinline__ unsigned pk2c(float a, float b) { const f32x2_ v = {a, b}; const bf16x2_ r = __builtin_convertvector(v, bf16x2_); return __builtin_bit_cast(unsigned, r); }
; #define MFMA16(a, b, c) __builtin_amdgcn_mfma_f32_16x16x32_bf16((a), (b), (c), 0, 0, 0)
; __device__ __forceinline__ void phase_prep(const Args& a, PG8_LAS unsigned char* lds) {
;     ...
;         {
;             bf16x8 tf[4][2];
; #pragma unroll
;             for (int it = 0; it < 4; ++it)
; #pragma unroll
;                 for (int s = 0; s < 2; ++s) tf[it][s] = *(const PG8_LAS bf16x8*)(Tu + ((16 * it + r) * 72 + 32 * s + 8 * q) * 2);
; #pragma unroll
;             for (int cc = 0; cc < 2; ++cc) { const int ct = 2 * lw + cc;
;                 const bf16x8 v0 = pv[cc][0], v1 = pv[cc][1];
; #pragma unroll
;                 for (int it = 0; it < 4; ++it) { f32x4 acc = {0.f, 0.f, 0.f, 0.f}; acc = MFMA16(tf[it][0], v0, acc); acc = MFMA16(tf[it][1], v1, acc);
;                     u32x2 w; w.x = pk2c(acc[0], acc[1]); w.y = pk2c(acc[2], acc[3]);
;                     *(u32x2*)(uT + (16 * ct + r) * 64 + 16 * it + 4 * q) = w; } }
; #pragma unroll
;             for (int it = 0; it < 4; ++it)
; #pragma unroll
;                 for (int s = 0; s < 2; ++s) tf[it][s] = *(const PG8_LAS bf16x8*)(Tw + ((16 * it + r) * 72 + 32 * s + 8 * q) * 2);
; #pragma unroll
;             for (int cc = 0; cc < 2; ++cc) { const int dt = 2 * lw + cc;
;                 const bf16x8 k0 = pk[cc][0], k1 = pk[cc][1];
;                 const int o4 = 16 * dt + 4 * q, dpos = (o4 & ~31) + perm32s(o4 & 31);
; #pragma unroll
;                 for (int it = 0; it < 4; ++it) { f32x4 acc = {0.f, 0.f, 0.f, 0.f}; acc = MFMA16(k0, tf[it][0], acc); acc = MFMA16(k1, tf[it][1], acc);
;                     u32x2 w; w.x = pk2c(acc[0], acc[1]); w.y = pk2c(acc[2], acc[3]);
;                     *(u32x2*)(wp + (16 * it + r) * 128 + dpos) = w; } }
;         }
;         __syncthreads();
;     }
.LBB0_252:
	s_waitcnt lgkmcnt(0)
	s_barrier
	ds_read_b128 v[32:35], v228 offset:17408
	ds_read_b128 v[36:39], v228 offset:17472
	ds_read_b128 v[44:47], v228 offset:19712
	ds_read_b128 v[48:51], v228 offset:19776
	ds_read_b128 v[56:59], v228 offset:22016
	ds_read_b128 v[60:63], v228 offset:22080
	s_waitcnt vmcnt(7) lgkmcnt(5)
	v_mfma_f32_16x16x32_bf16 v[40:43], v[32:35], v[0:3], 0
	ds_read_b128 v[68:71], v228 offset:24320
	ds_read_b128 v[72:75], v228 offset:24384
	v_mov_b32_e32 v113, v97
	s_waitcnt vmcnt(3)
	v_mfma_f32_16x16x32_bf16 v[32:35], v[32:35], v[20:23], 0
	v_mov_b32_e32 v115, v97
	s_mov_b64 s[20:21], 0xc000
	v_mov_b32_e32 v117, v97
	s_waitcnt lgkmcnt(6)
	v_mfma_f32_16x16x32_bf16 v[40:43], v[36:39], v[4:7], v[40:43]
	v_mov_b32_e32 v121, v97
	v_mov_b32_e32 v123, v97
	v_mov_b32_e32 v119, v97
	s_waitcnt lgkmcnt(5)
	v_mfma_f32_16x16x32_bf16 v[52:55], v[44:47], v[0:3], 0
	v_mov_b32_e32 v125, v97
	s_add_i32 s38, s38, 1
	s_add_i32 s31, s31, s34
	s_waitcnt vmcnt(2)
	v_mfma_f32_16x16x32_bf16 v[32:35], v[36:39], v[28:31], v[32:35]
	v_lshl_add_u64 v[36:37], s[18:19], 0, v[112:113]
	v_lshl_add_u64 v[80:81], v[36:37], 0, v[114:115]
	v_lshl_add_u64 v[82:83], v[80:81], 0, s[20:21]
	s_waitcnt lgkmcnt(3)
	v_mfma_f32_16x16x32_bf16 v[64:67], v[56:59], v[0:3], 0
	s_cmp_lt_i32 s38, s98
	v_mfma_f32_16x16x32_bf16 v[36:39], v[44:47], v[20:23], 0
	v_cvt_pk_bf16_f32 v44, v40, v41
	v_cvt_pk_bf16_f32 v45, v42, v43
	v_add_co_u32_e32 v46, vcc, s35, v80
	v_mfma_f32_16x16x32_bf16 v[40:43], v[56:59], v[20:23], 0
	s_nop 0
	v_addc_co_u32_e32 v47, vcc, 0, v81, vcc
	global_store_dwordx2 v[46:47], v[44:45], off
	v_mfma_f32_16x16x32_bf16 v[52:55], v[48:51], v[4:7], v[52:55]
	v_lshl_add_u64 v[80:81], s[18:19], 0, v[116:117]
	s_waitcnt lgkmcnt(2)
	v_mfma_f32_16x16x32_bf16 v[64:67], v[60:63], v[4:7], v[64:67]
	v_mfma_f32_16x16x32_bf16 v[40:43], v[60:63], v[28:31], v[40:43]
	v_cvt_pk_bf16_f32 v60, v32, v33
	v_cvt_pk_bf16_f32 v61, v34, v35
	ds_read_b128 v[32:35], v228 offset:28928
	v_mfma_f32_16x16x32_bf16 v[36:39], v[48:51], v[28:31], v[36:39]
	v_cvt_pk_bf16_f32 v44, v52, v53
	v_cvt_pk_bf16_f32 v45, v54, v55
	global_store_dwordx2 v[82:83], v[44:45], off offset:32
	s_waitcnt lgkmcnt(2)
	v_mfma_f32_16x16x32_bf16 v[76:79], v[68:71], v[0:3], 0
	global_store_dwordx2 v[82:83], v[60:61], off offset:2048
	ds_read_b128 v[60:63], v228 offset:28992
	v_cvt_pk_bf16_f32 v48, v64, v65
	v_mfma_f32_16x16x32_bf16 v[44:47], v[68:71], v[20:23], 0
	v_cvt_pk_bf16_f32 v49, v66, v67
	v_cvt_pk_bf16_f32 v36, v36, v37
	v_cvt_pk_bf16_f32 v37, v38, v39
	s_waitcnt lgkmcnt(1)
	v_mfma_f32_16x16x32_bf16 v[64:67], v[8:11], v[32:35], 0
	global_store_dwordx2 v[82:83], v[36:37], off offset:2080
	ds_read_b128 v[36:39], v228 offset:31232
	global_store_dwordx2 v[82:83], v[48:49], off offset:64
	s_waitcnt vmcnt(6)
	v_mfma_f32_16x16x32_bf16 v[32:35], v[16:19], v[32:35], 0
	ds_read_b128 v[48:51], v228 offset:26624
	v_mfma_f32_16x16x32_bf16 v[76:79], v[72:75], v[4:7], v[76:79]
	v_mfma_f32_16x16x32_bf16 v[44:47], v[72:75], v[28:31], v[44:47]
	v_cvt_pk_bf16_f32 v72, v40, v41
	v_cvt_pk_bf16_f32 v73, v42, v43
	global_store_dwordx2 v[82:83], v[72:73], off offset:2112
	ds_read_b128 v[72:75], v228 offset:33536
	s_waitcnt lgkmcnt(3)
	v_mfma_f32_16x16x32_bf16 v[64:67], v[12:15], v[60:63], v[64:67]
	s_nop 0
	v_cvt_pk_bf16_f32 v52, v76, v77
	v_cvt_pk_bf16_f32 v53, v78, v79
	ds_read_b128 v[40:43], v228 offset:31296
	s_waitcnt vmcnt(6)
	v_mfma_f32_16x16x32_bf16 v[32:35], v[24:27], v[60:63], v[32:35]
	v_cvt_pk_bf16_f32 v44, v44, v45
	v_cvt_pk_bf16_f32 v45, v46, v47
	global_store_dwordx2 v[82:83], v[52:53], off offset:96
	ds_read_b128 v[52:55], v228 offset:26688
	s_waitcnt lgkmcnt(4)
	v_mfma_f32_16x16x32_bf16 v[68:71], v[8:11], v[36:39], 0
	global_store_dwordx2 v[82:83], v[44:45], off offset:2144
	ds_read_b128 v[44:47], v228 offset:33600
	v_cvt_pk_bf16_f32 v64, v64, v65
	v_mfma_f32_16x16x32_bf16 v[36:39], v[16:19], v[36:39], 0
	v_cvt_pk_bf16_f32 v65, v66, v67
	v_cvt_pk_bf16_f32 v66, v32, v33
	v_cvt_pk_bf16_f32 v67, v34, v35
	s_waitcnt lgkmcnt(4)
	v_mfma_f32_16x16x32_bf16 v[56:59], v[8:11], v[48:51], 0
	v_lshl_add_u64 v[82:83], v[80:81], 0, v[118:119]
	v_lshl_add_u64 v[60:61], v[80:81], 0, v[124:125]
	s_waitcnt lgkmcnt(3)
	v_mfma_f32_16x16x32_bf16 v[76:79], v[8:11], v[72:75], 0
	v_mfma_f32_16x16x32_bf16 v[48:51], v[16:19], v[48:51], 0
	v_mfma_f32_16x16x32_bf16 v[32:35], v[16:19], v[72:75], 0
	s_waitcnt lgkmcnt(2)
	v_mfma_f32_16x16x32_bf16 v[68:71], v[12:15], v[40:43], v[68:71]
	v_mfma_f32_16x16x32_bf16 v[36:39], v[24:27], v[40:43], v[36:39]
	s_waitcnt lgkmcnt(1)
	v_mfma_f32_16x16x32_bf16 v[56:59], v[12:15], v[52:55], v[56:59]
	s_waitcnt lgkmcnt(0)
	v_mfma_f32_16x16x32_bf16 v[76:79], v[12:15], v[44:47], v[76:79]
	v_mfma_f32_16x16x32_bf16 v[48:51], v[24:27], v[52:55], v[48:51]
	v_lshl_add_u64 v[54:55], v[80:81], 0, v[120:121]
	s_nop 0
	v_cvt_pk_bf16_f32 v52, v68, v69
	v_cvt_pk_bf16_f32 v53, v70, v71
	v_mfma_f32_16x16x32_bf16 v[32:35], v[24:27], v[44:47], v[32:35]
	v_lshl_add_u64 v[70:71], v[80:81], 0, v[122:123]
	global_store_dwordx4 v[54:55], v[64:67], off
	v_cvt_pk_bf16_f32 v54, v36, v37
	v_cvt_pk_bf16_f32 v55, v38, v39
	v_cvt_pk_bf16_f32 v56, v56, v57
	v_cvt_pk_bf16_f32 v57, v58, v59
	v_cvt_pk_bf16_f32 v68, v76, v77
	v_cvt_pk_bf16_f32 v69, v78, v79
	v_cvt_pk_bf16_f32 v58, v48, v49
	v_cvt_pk_bf16_f32 v59, v50, v51
	global_store_dwordx4 v[70:71], v[52:55], off
	v_cvt_pk_bf16_f32 v70, v32, v33
	v_cvt_pk_bf16_f32 v71, v34, v35
	global_store_dwordx4 v[82:83], v[56:59], off
	global_store_dwordx4 v[60:61], v[68:71], off
	s_barrier
	s_cbranch_scc0 .LBB0_300
